# grid-barrier poll loops spin without s_sleep (s_nop 0) on top of v41
# speedup vs baseline: 1.0061x; 1.0061x over previous
; __global__ void __launch_bounds__(512, 2) fwd_kernel(Params p_unused) {
;     ...
;     grid.sync();
.LBB0_147:
	s_nop 0
	global_load_dword v2, v0, s[2:3] offset:32 sc1
	s_waitcnt vmcnt(0)
	v_and_b32_e32 v2, 0xffff0000, v2
	v_cmp_ne_u32_e32 vcc, v2, v1
	s_or_b64 s[4:5], vcc, s[4:5]
	s_andn2_b64 exec, exec, s[4:5]
	s_cbranch_execnz .LBB0_147

; __device__ __forceinline__ unsigned xb_ld(unsigned* p)              { return __hip_atomic_load(p, __ATOMIC_RELAXED, __HIP_MEMORY_SCOPE_AGENT); }
; __device__ __forceinline__ void xcd_barrier_complete(unsigned* bar, unsigned x, unsigned& nloc, unsigned& nx) {
;     ...
;     for (;;) {
;         sum = 0u; cnt = 0u; mine = 0u;
; #pragma unroll
;         for (unsigned j = 0; j < 16; ++j) { const unsigned c = xb_ld(&bar[XB_XCNT(j)]); sum += c; cnt += (c > 0u) ? 1u : 0u; mine = (j == x) ? c : mine; }
;         if (sum == G) break;
;         __builtin_amdgcn_s_sleep(1);
;         if ((++sp & 255u) == 0u) { if (xb_ld(&bar[XB_TMO])) break; if (sp > XB_SPIN_CAP) { atomicAdd(&bar[XB_TMO], 1u); break; } }
;     }
.LBB0_638:
	global_load_dword v15, v169, s[4:5] offset:1024 sc1
	s_waitcnt lgkmcnt(0)
	global_load_dword v0, v169, s[4:5] offset:1280 sc1
	global_load_dword v1, v169, s[4:5] offset:1536 sc1
	global_load_dword v2, v169, s[4:5] offset:1792 sc1
	global_load_dword v3, v169, s[4:5] offset:2048 sc1
	global_load_dword v4, v169, s[4:5] offset:2304 sc1
	global_load_dword v5, v169, s[4:5] offset:2560 sc1
	global_load_dword v6, v169, s[4:5] offset:2816 sc1
	global_load_dword v7, v169, s[4:5] offset:3072 sc1
	global_load_dword v8, v169, s[4:5] offset:3328 sc1
	global_load_dword v9, v169, s[4:5] offset:3584 sc1
	global_load_dword v10, v169, s[4:5] offset:3840 sc1
	global_load_dword v11, v169, s[6:7] sc1
	global_load_dword v12, v169, s[8:9] sc1
	global_load_dword v13, v169, s[10:11] sc1
	global_load_dword v14, v169, s[12:13] sc1
	s_mov_b64 s[14:15], -1
	s_mov_b64 s[16:17], -1
	s_waitcnt vmcnt(14)
	v_add_u32_e32 v16, v0, v15
	s_waitcnt vmcnt(13)
	v_add_u32_e32 v16, v16, v1
	s_waitcnt vmcnt(12)
	v_add_u32_e32 v16, v16, v2
	s_waitcnt vmcnt(11)
	v_add_u32_e32 v16, v16, v3
	s_waitcnt vmcnt(10)
	v_add_u32_e32 v16, v16, v4
	s_waitcnt vmcnt(9)
	v_add_u32_e32 v16, v16, v5
	s_waitcnt vmcnt(8)
	v_add_u32_e32 v16, v16, v6
	s_waitcnt vmcnt(7)
	v_add_u32_e32 v16, v16, v7
	s_waitcnt vmcnt(6)
	v_add_u32_e32 v16, v16, v8
	s_waitcnt vmcnt(5)
	v_add_u32_e32 v16, v16, v9
	s_waitcnt vmcnt(4)
	v_add_u32_e32 v16, v16, v10
	s_waitcnt vmcnt(3)
	v_add_u32_e32 v16, v16, v11
	s_waitcnt vmcnt(2)
	v_add_u32_e32 v16, v16, v12
	s_waitcnt vmcnt(1)
	v_add_u32_e32 v16, v16, v13
	s_waitcnt vmcnt(0)
	v_add_u32_e32 v16, v16, v14
	v_cmp_eq_u32_e32 vcc, s91, v16
	s_cbranch_vccnz .LBB0_637
	s_and_b32 s14, s20, 0xff
	s_cmp_eq_u32 s14, 0
	s_mov_b64 s[14:15], -1
	s_mov_b64 s[18:19], -1
	s_nop 0
	s_cbranch_scc0 .LBB0_642
	global_load_dword v16, v169, s[4:5] offset:512 sc1
	s_waitcnt vmcnt(0)
	v_cmp_eq_u32_e32 vcc, 0, v16
	s_cbranch_vccnz .LBB0_644
	s_mov_b64 s[18:19], 0

; __device__ __forceinline__ unsigned xb_ld(unsigned* p)              { return __hip_atomic_load(p, __ATOMIC_RELAXED, __HIP_MEMORY_SCOPE_AGENT); }
; __device__ __forceinline__ unsigned xb_add(unsigned* p, unsigned v) { return __hip_atomic_fetch_add(p, v, __ATOMIC_RELAXED, __HIP_MEMORY_SCOPE_AGENT); }
; #define XB_SPIN(cond, bar) do { unsigned _sp = 0; while (cond) { __builtin_amdgcn_s_sleep(1); \
;     if ((++_sp & 255u) == 0u) { if (xb_ld(&(bar)[XB_TMO])) break; if (_sp > XB_SPIN_CAP) { atomicAdd(&(bar)[XB_TMO], 1u); break; } } } } while (0)
; __device__ __forceinline__ void xcd_barrier(unsigned* bar, volatile LAS unsigned* st) {
;     ...
;             if (og + 1u == (tg + 1u) * nx) xb_add(&bar[XB_TOPGEN], 1u);
;             else XB_SPIN(xb_ld(&bar[XB_TOPGEN]) == tg, bar);
;             __builtin_amdgcn_fence(__ATOMIC_ACQUIRE, "agent");
;             xb_add(&bar[XB_XGEN(x)], 1u);
;             asm volatile("s_waitcnt vmcnt(0)" ::: "memory");
;         } else {
;             XB_SPIN(xb_ld(&bar[XB_XGEN(x)]) == gen, bar);
.LBB0_656:
	s_and_b32 s20, s2, 0xff
	s_mov_b64 s[18:19], -1
	s_cmp_lg_u32 s20, 0
	s_mov_b64 s[22:23], -1
	s_nop 0
	s_cbranch_scc1 .LBB0_659
	global_load_dword v0, v169, s[4:5] offset:512 sc1
	s_waitcnt vmcnt(0)
	v_cmp_eq_u32_e32 vcc, 0, v0
	s_cbranch_vccnz .LBB0_661
	s_mov_b64 s[22:23], 0
	s_mov_b64 s[20:21], -1

; __device__ __forceinline__ unsigned xb_ld(unsigned* p)              { return __hip_atomic_load(p, __ATOMIC_RELAXED, __HIP_MEMORY_SCOPE_AGENT); }
; __device__ __forceinline__ unsigned xb_add(unsigned* p, unsigned v) { return __hip_atomic_fetch_add(p, v, __ATOMIC_RELAXED, __HIP_MEMORY_SCOPE_AGENT); }
; #define XB_SPIN(cond, bar) do { unsigned _sp = 0; while (cond) { __builtin_amdgcn_s_sleep(1); \
;     if ((++_sp & 255u) == 0u) { if (xb_ld(&(bar)[XB_TMO])) break; if (_sp > XB_SPIN_CAP) { atomicAdd(&(bar)[XB_TMO], 1u); break; } } } } while (0)
; __device__ __forceinline__ void xcd_barrier(unsigned* bar, volatile LAS unsigned* st) {
;     ...
;             if (og + 1u == (tg + 1u) * nx) xb_add(&bar[XB_TOPGEN], 1u);
;             else XB_SPIN(xb_ld(&bar[XB_TOPGEN]) == tg, bar);
;             __builtin_amdgcn_fence(__ATOMIC_ACQUIRE, "agent");
;             xb_add(&bar[XB_XGEN(x)], 1u);
;             asm volatile("s_waitcnt vmcnt(0)" ::: "memory");
;         } else {
;             XB_SPIN(xb_ld(&bar[XB_XGEN(x)]) == gen, bar);
.LBB0_673:
	s_and_b32 s20, s2, 0xff
	s_mov_b64 s[18:19], -1
	s_cmp_lg_u32 s20, 0
	s_mov_b64 s[22:23], -1
	s_nop 0
	s_cbranch_scc1 .LBB0_676
	global_load_dword v0, v169, s[12:13] sc1
	s_waitcnt vmcnt(0)
	v_cmp_eq_u32_e32 vcc, 0, v0
	s_cbranch_vccnz .LBB0_678
	s_mov_b64 s[22:23], 0
	s_mov_b64 s[20:21], -1
